# GEMM K-loop: first-iteration vmcnt waits after a tile epilogue counted exactly (epilogue stores and SS prefetch loads no longer forced to drain before segment 1/2) in Down and GU GEMMs
# baseline (speedup 1.0000x reference)
; #define PG8_STAGE(bufoff, gbase, voff) do { _Pragma("unroll") for (int _i = 0; _i < 2; ++_i) \
;         __builtin_amdgcn_global_load_lds((const unsigned*)((const char*)(gbase) + (voff)[_i]), (PG8_LAS unsigned*)(lds + (bufoff) + ldsw + _i * 8192), 16, 0, 0); } while (0)
; #define PG8_WAIT_V(n) asm volatile("s_waitcnt vmcnt(" #n ")" ::: "memory")
; #define PG8_BAR __builtin_amdgcn_s_barrier()
; template <class Epi, class Sched, bool ALIGN_EPI = false, bool SP2 = false>
; __device__ __forceinline__ void gemm_phase(PG8_LAS unsigned char* lds, const Gemm g, const Sched& S, const Epi& E) {
;     ...
;     for (int i = 0; i < 2; ++i) { int R, C; stage_rc(tid * 16 + i * 8192, R, C); const int Rb = Epi::PERM ? ((R & ~31) + perm32(R & 31)) : R;
;         voffA[i] = (unsigned)(R * K + C) * 2u; voffB[i] = (unsigned)(Rb * K + C) * 2u; }
;     const size_t kstep = (size_t)(BK * 2);
;     const size_t hstep = (size_t)HALF * K * 2;
;     const size_t tstep = 2 * hstep;
;     const unsigned ldsw = (unsigned)wid * 1024u;
;     const int aoff = lds_byte(wr * 64 + fr, fq * 8), boff = lds_byte(wc * 32 + fr, fq * 8);
;     ...
;     Unit cur, nxt; int ui = 0;
;     if (!S.next(0, cur)) return;
;     f32x4 acc[2][2][4][2];
; #pragma unroll
;     for (int a = 0; a < 2; ++a)
; #pragma unroll
;         for (int b = 0; b < 2; ++b)
; #pragma unroll
;             for (int m = 0; m < 4; ++m)
; #pragma unroll
;                 for (int n = 0; n < 2; ++n) acc[a][b][m][n] = (f32x4){0.f, 0.f, 0.f, 0.f};
;     bf16x8 At[4][2], B0[2][2], B1[2][2];
;     const char* cA = (const char*)g.A + (size_t)cur.pm * tstep; const char* cB = (const char*)g.Bt + (size_t)cur.pn * tstep;
;     S.a_ready(cur);
;     if constexpr (SP2) {
;         PG8_STAGE(PG8_SB(0, 0), cB, voffB); PG8_STAGE(PG8_SB(0, 1), cB + hstep, voffB); PG8_STAGE(PG8_SA(0, 0), cA, voffA); PG8_STAGE(PG8_SA(0, 1), cA + hstep, voffA);
;         if (wr == 1) PG8_BAR;
;         PG8_WAIT_V(2); PG8_BAR;
;         PG8_STAGE(PG8_SB(1, 0), cB + kstep, voffB); PG8_STAGE(PG8_SA(1, 0), cA + kstep, voffA); PG8_STAGE(PG8_SB(1, 1), cB + hstep + kstep, voffB);
;         PG8_WAIT_V(6); PG8_BAR;
.LBB0_168:
	s_lshl_b32 s1, s1, 5
	s_and_b32 s64, s1, 0x60
	s_add_i32 m0, s40, 0x18000
	v_lshl_add_u64 v[8:9], v[8:9], 0, s[28:29]
	s_lshl_b32 s61, s6, 6
	s_lshl_b32 s8, s6, 13
	s_lshl_b32 s1, s64, 7
	s_waitcnt vmcnt(2)
	s_barrier
	global_load_lds_dwordx4 v[8:9], off
	v_lshl_add_u64 v[6:7], v[6:7], 0, s[28:29]
	s_add_i32 m0, s40, 0x1a000
	s_add_i32 s65, s40, 0x8000
	s_add_i32 s69, s40, 0xa000
	global_load_lds_dwordx4 v[6:7], off
	v_lshl_add_u64 v[2:3], v[2:3], 0, s[28:29]
	s_mov_b32 m0, s65
	s_add_u32 s6, s24, 0x40080
	global_load_lds_dwordx4 v[2:3], off
	v_lshl_add_u64 v[2:3], v[4:5], 0, s[28:29]
	s_mov_b32 m0, s69
	s_addc_u32 s7, s25, 0
	global_load_lds_dwordx4 v[2:3], off
	s_add_i32 m0, s40, 0x1c000
	v_lshl_add_u64 v[2:3], s[6:7], 0, v[0:1]
	global_load_lds_dwordx4 v[2:3], off
	v_lshl_add_u64 v[2:3], s[6:7], 0, v[130:131]
	s_add_i32 m0, s40, 0x1e000
	s_movk_i32 s6, 0x3c0
	global_load_lds_dwordx4 v[2:3], off
	v_and_b32_e32 v2, 48, v10
	v_lshlrev_b32_e32 v3, 6, v10
	v_and_or_b32 v2, v3, s6, v2
	v_lshlrev_b32_e32 v3, 2, v10
	v_and_b32_e32 v3, 32, v3
	v_bitop3_b32 v4, v2, s8, v3 bitop3:0xde
	v_bitop3_b32 v144, s1, v2, v3 bitop3:0xf6
	v_lshlrev_b32_e32 v2, 14, v11
	v_and_b32_e32 v2, 0xffff8000, v2
	v_lshl_add_u32 v2, v12, 11, v2
	v_and_b32_e32 v3, 1, v11
	v_lshl_or_b32 v2, v3, 6, v2
	v_lshl_add_u32 v136, v13, 1, v2
	v_lshlrev_b32_e32 v2, 14, v15
	v_and_b32_e32 v2, 0xffff8000, v2
	s_waitcnt vmcnt(6)
	v_lshl_add_u32 v2, v14, 11, v2
	v_and_b32_e32 v3, 1, v15
	s_cmpk_lt_u32 s0, 0x100
	v_lshl_or_b32 v2, v3, 6, v2
	v_readlane_b32 s0, v253, 56
	s_cselect_b64 s[6:7], -1, 0
	v_mov_b32_e32 v137, v1
	v_lshl_add_u32 v138, v16, 1, v2
	v_mov_b32_e32 v139, v1
	s_mov_b32 s70, 0
	v_add_u32_e32 v145, 0, v4
	v_readlane_b32 s71, v253, 55
	s_mov_b32 s72, s0
	s_barrier
	v_readlane_b32 s1, v253, 57
	s_mov_b32 s83, 1
	s_branch .LBB0_171

;     __device__ __forceinline__ void operator()(const f32x4 (&acc)[2][2][4][2], const Unit& u, int wr, int wc, int fr_in, int fq_in) const {
;     ...
;         for (int ai = 0; ai < 2; ++ai)
; #pragma unroll
;             for (int m = 0; m < 4; ++m) ssv[ai][m] = SS[row0 + ai * HALF + m * 16];
; template <class Epi, class Sched, bool ALIGN_EPI = false, bool SP2 = false>
; __device__ __forceinline__ void gemm_phase(PG8_LAS unsigned char* lds, const Gemm g, const Sched& S, const Epi& E) {
;     ...
; #pragma unroll
;         for (int a = 0; a < 2; ++a)
; #pragma unroll
;             for (int b = 0; b < 2; ++b)
; #pragma unroll
;                 for (int m = 0; m < 4; ++m)
; #pragma unroll
;                     for (int n = 0; n < 2; ++n) acc[a][b][m][n] = (f32x4){0.f, 0.f, 0.f, 0.f};
;         cur = nxt; cA = nA; cB = nB; ++ui;
.LBB0_177:
	s_ashr_i32 s19, s18, 31
	s_lshl_b64 s[8:9], s[18:19], 19
	s_add_u32 s22, s58, s8
	s_addc_u32 s23, s59, s9
	s_and_b64 s[8:9], s[0:1], exec
	s_cselect_b32 s19, s23, s27
	s_cselect_b32 s73, s22, s26
	s_ashr_i32 s15, s14, 31
	s_lshl_b64 s[8:9], s[14:15], 19
	s_add_u32 s8, s30, s8
	s_addc_u32 s9, s39, s9
	s_and_b64 s[36:37], s[0:1], exec
	s_cselect_b32 s15, s9, s25
	s_cselect_b32 s74, s8, s24
	s_add_u32 s75, s24, 0x100
	s_addc_u32 s76, s25, 0
	s_add_u32 s24, s26, 0x40080
	v_mov_b32_e32 v2, 0
	s_addc_u32 s25, s27, 0
	s_mov_b32 s77, -2
	v_mov_b32_e32 v3, v2
	v_mov_b32_e32 v4, v2
	v_mov_b32_e32 v5, v2
	v_mov_b32_e32 v10, v2
	v_mov_b32_e32 v11, v2
	v_mov_b32_e32 v12, v2
	v_mov_b32_e32 v13, v2
	v_mov_b32_e32 v22, v2
	v_mov_b32_e32 v23, v2
	v_mov_b32_e32 v24, v2
	v_mov_b32_e32 v25, v2
	v_mov_b32_e32 v26, v2
	v_mov_b32_e32 v27, v2
	v_mov_b32_e32 v28, v2
	v_mov_b32_e32 v29, v2
	v_mov_b32_e32 v38, v2
	v_mov_b32_e32 v39, v2
	v_mov_b32_e32 v40, v2
	v_mov_b32_e32 v41, v2
	v_mov_b32_e32 v42, v2
	v_mov_b32_e32 v43, v2
	v_mov_b32_e32 v44, v2
	v_mov_b32_e32 v45, v2
	v_mov_b32_e32 v54, v2
	v_mov_b32_e32 v55, v2
	v_mov_b32_e32 v56, v2
	v_mov_b32_e32 v57, v2
	v_mov_b32_e32 v58, v2
	v_mov_b32_e32 v59, v2
	v_mov_b32_e32 v60, v2
	v_mov_b32_e32 v61, v2
	v_mov_b32_e32 v6, v2
	v_mov_b32_e32 v7, v2
	v_mov_b32_e32 v8, v2
	v_mov_b32_e32 v9, v2
	v_mov_b32_e32 v14, v2
	v_mov_b32_e32 v15, v2
	v_mov_b32_e32 v16, v2
	v_mov_b32_e32 v17, v2
	v_mov_b32_e32 v18, v2
	v_mov_b32_e32 v19, v2
	v_mov_b32_e32 v20, v2
	v_mov_b32_e32 v21, v2
	v_mov_b32_e32 v30, v2
	v_mov_b32_e32 v31, v2
	v_mov_b32_e32 v32, v2
	v_mov_b32_e32 v33, v2
	v_mov_b32_e32 v34, v2
	v_mov_b32_e32 v35, v2
	v_mov_b32_e32 v36, v2
	v_mov_b32_e32 v37, v2
	v_mov_b32_e32 v46, v2
	v_mov_b32_e32 v47, v2
	v_mov_b32_e32 v48, v2
	v_mov_b32_e32 v49, v2
	v_mov_b32_e32 v50, v2
	v_mov_b32_e32 v51, v2
	v_mov_b32_e32 v52, v2
	v_mov_b32_e32 v53, v2
	v_mov_b32_e32 v62, v2
	v_mov_b32_e32 v63, v2
	v_mov_b32_e32 v64, v2
	v_mov_b32_e32 v65, v2
	v_mov_b32_e32 v70, v2
	v_mov_b32_e32 v71, v2
	v_mov_b32_e32 v72, v2
	v_mov_b32_e32 v73, v2
	v_mov_b32_e32 v74, v2
	v_mov_b32_e32 v75, v2
	v_mov_b32_e32 v76, v2
	v_mov_b32_e32 v77, v2
	v_mov_b32_e32 v86, v2
	v_mov_b32_e32 v87, v2
	v_mov_b32_e32 v88, v2
	v_mov_b32_e32 v89, v2
	v_mov_b32_e32 v90, v2
	v_mov_b32_e32 v91, v2
	v_mov_b32_e32 v92, v2
	v_mov_b32_e32 v93, v2
	v_mov_b32_e32 v102, v2
	v_mov_b32_e32 v103, v2
	v_mov_b32_e32 v104, v2
	v_mov_b32_e32 v105, v2
	v_mov_b32_e32 v110, v2
	v_mov_b32_e32 v111, v2
	v_mov_b32_e32 v112, v2
	v_mov_b32_e32 v113, v2
	v_mov_b32_e32 v114, v2
	v_mov_b32_e32 v115, v2
	v_mov_b32_e32 v116, v2
	v_mov_b32_e32 v117, v2
	v_mov_b32_e32 v122, v2
	v_mov_b32_e32 v123, v2
	v_mov_b32_e32 v124, v2
	v_mov_b32_e32 v125, v2
	v_mov_b32_e32 v66, v2
	v_mov_b32_e32 v67, v2
	v_mov_b32_e32 v68, v2
	v_mov_b32_e32 v69, v2
	v_mov_b32_e32 v78, v2
	v_mov_b32_e32 v79, v2
	v_mov_b32_e32 v80, v2
	v_mov_b32_e32 v81, v2
	v_mov_b32_e32 v82, v2
	v_mov_b32_e32 v83, v2
	v_mov_b32_e32 v84, v2
	v_mov_b32_e32 v85, v2
	v_mov_b32_e32 v94, v2
	v_mov_b32_e32 v95, v2
	v_mov_b32_e32 v96, v2
	v_mov_b32_e32 v97, v2
	v_mov_b32_e32 v98, v2
	v_mov_b32_e32 v99, v2
	v_mov_b32_e32 v100, v2
	v_mov_b32_e32 v101, v2
	v_mov_b32_e32 v106, v2
	v_mov_b32_e32 v107, v2
	v_mov_b32_e32 v108, v2
	v_mov_b32_e32 v109, v2
	v_mov_b32_e32 v118, v2
	v_mov_b32_e32 v119, v2
	v_mov_b32_e32 v120, v2
	v_mov_b32_e32 v121, v2
	v_mov_b32_e32 v126, v2
	v_mov_b32_e32 v127, v2
	v_mov_b32_e32 v128, v2
	v_mov_b32_e32 v129, v2
	v_mov_b32_e32 v224, s72
	v_lshl_add_u32 v224, v224, 8, s61
	v_and_or_b32 v224, v252, 15, v224
	v_ashrrev_i32_e32 v225, 31, v224
	v_lshl_add_u64 v[226:227], v[224:225], 2, s[12:13]
	global_load_dword v232, v[226:227], off
	global_load_dword v233, v[226:227], off offset:64
	global_load_dword v234, v[226:227], off offset:128
	global_load_dword v235, v[226:227], off offset:192
	global_load_dword v236, v[226:227], off offset:512
	global_load_dword v237, v[226:227], off offset:576
	global_load_dword v238, v[226:227], off offset:640
	global_load_dword v239, v[226:227], off offset:704
	s_mov_b32 s82, s83
; #define PG8_STAGE(bufoff, gbase, voff) do { _Pragma("unroll") for (int _i = 0; _i < 2; ++_i) \
;         __builtin_amdgcn_global_load_lds((const unsigned*)((const char*)(gbase) + (voff)[_i]), (PG8_LAS unsigned*)(lds + (bufoff) + ldsw + _i * 8192), 16, 0, 0); } while (0)
; #define PG8_LDA(dst, b, h) do { _Pragma("unroll") for (int m = 0; m < 4; ++m) _Pragma("unroll") for (int k = 0; k < 2; ++k) dst[m][k] = *(const PG8_LAS bf16x8*)(lds + PG8_SA(b, h) + aoff + m * 2048 + k * 1024); } while (0)
; #define PG8_LDB(dst, b, h) do { _Pragma("unroll") for (int n = 0; n < 2; ++n) _Pragma("unroll") for (int k = 0; k < 2; ++k) dst[n][k] = *(const PG8_LAS bf16x8*)(lds + PG8_SB(b, h) + boff + n * 2048 + k * 1024); } while (0)
; #define PG8_MMA(ai, bj, At, Bt) do { __builtin_amdgcn_s_setprio(1); _Pragma("unroll") for (int m = 0; m < 4; ++m) _Pragma("unroll") for (int n = 0; n < 2; ++n) _Pragma("unroll") for (int k = 0; k < 2; ++k) \
;         acc[ai][bj][m][n] = __builtin_amdgcn_mfma_f32_16x16x32_bf16(Bt[n][k], At[m][k], acc[ai][bj][m][n], 0, 0, 0); __builtin_amdgcn_s_setprio(0); } while (0)
; #define PG8_WAIT_V(n) asm volatile("s_waitcnt vmcnt(" #n ")" ::: "memory")
; #define PG8_WAIT_L(n) asm volatile("s_waitcnt lgkmcnt(" #n ")" ::: "memory")
; #define PG8_BAR __builtin_amdgcn_s_barrier()
; #define PG8_SCHED __builtin_amdgcn_sched_barrier(0)
; template <class Epi, class Sched, bool ALIGN_EPI = false, bool SP2 = false>
; __device__ __forceinline__ void gemm_phase(PG8_LAS unsigned char* lds, const Gemm g, const Sched& S, const Epi& E) {
;     ...
;             PG8_LDB(B0, 0, 0); PG8_LDB(B1, 0, 1); PG8_SCHED; PG8_LDA(At, 0, 0); PG8_STAGE(PG8_SA(1, 1), a1 + hstep, voffA);
;             PG8_WAIT_V(8); PG8_WAIT_L(0); PG8_BAR; PG8_MMA(0, 0, At, B0); PG8_MMA(0, 1, At, B1); PG8_BAR; PG8_SCHED;
;             PG8_LDA(At, 0, 1); PG8_STAGE(PG8_SB(0, 0), b2, voffB); PG8_STAGE(PG8_SB(0, 1), b2 + hstep, voffB); PG8_STAGE(PG8_SA(0, 0), a2, voffA);
;             PG8_WAIT_V(8); PG8_WAIT_L(0); PG8_BAR; PG8_MMA(1, 0, At, B0); PG8_MMA(1, 1, At, B1); PG8_BAR; PG8_SCHED;
.LBB0_178:
	s_add_u32 s26, s24, 0xfffc0080
	s_addc_u32 s27, s25, -1
	s_add_i32 s78, 0, 0x10000
	s_cmp_eq_u32 s77, 12
	s_cselect_b32 s37, s19, s27
	s_cselect_b32 s36, s73, s26
	s_cselect_b32 s27, s15, s76
	s_cselect_b32 s26, s74, s75
	s_add_i32 s80, 0, 0x14000
	v_add_u32_e32 v154, s78, v144
	v_add_u32_e32 v170, s80, v144
	ds_read_b128 v[140:143], v154
	ds_read_b128 v[146:149], v154 offset:1024
	ds_read_b128 v[150:153], v154 offset:2048
	ds_read_b128 v[154:157], v154 offset:3072
	ds_read_b128 v[158:161], v170
	ds_read_b128 v[162:165], v170 offset:1024
	ds_read_b128 v[166:169], v170 offset:2048
	ds_read_b128 v[170:173], v170 offset:3072
	v_lshl_add_u64 v[206:207], s[24:25], 0, v[138:139]
	s_add_i32 m0, s40, 0xc000
	ds_read_b128 v[174:177], v145
	ds_read_b128 v[178:181], v145 offset:1024
	ds_read_b128 v[182:185], v145 offset:2048
	ds_read_b128 v[186:189], v145 offset:3072
	ds_read_b128 v[190:193], v145 offset:4096
	ds_read_b128 v[194:197], v145 offset:5120
	ds_read_b128 v[198:201], v145 offset:6144
	ds_read_b128 v[202:205], v145 offset:7168
	global_load_lds_dwordx4 v[206:207], off
	v_lshl_add_u64 v[206:207], s[24:25], 0, v[136:137]
	s_add_i32 m0, s40, 0xe000
	s_nop 0
	global_load_lds_dwordx4 v[206:207], off
	s_cmp_eq_u32 s82, 0
	s_cbranch_scc1 .Lrw_gu_1_w8
	s_cmp_eq_u32 s82, 1
	s_cbranch_scc1 .Lrw_gu_1_w1
	s_waitcnt vmcnt(24)
	s_branch .Lrw_gu_1_done
.Lrw_gu_1_w1:
	s_waitcnt vmcnt(16)
	s_branch .Lrw_gu_1_done
.Lrw_gu_1_w8:
	s_waitcnt vmcnt(8)
.Lrw_gu_1_done:
	s_waitcnt lgkmcnt(0)
	s_barrier
	s_setprio 1
	s_waitcnt lgkmcnt(0)
	v_mfma_f32_16x16x32_bf16 v[126:129], v[140:143], v[174:177], v[126:129]
	v_mfma_f32_16x16x32_bf16 v[118:121], v[150:153], v[174:177], v[118:121]
	v_mfma_f32_16x16x32_bf16 v[106:109], v[140:143], v[182:185], v[106:109]
	v_mfma_f32_16x16x32_bf16 v[98:101], v[150:153], v[182:185], v[98:101]
	v_mfma_f32_16x16x32_bf16 v[94:97], v[140:143], v[190:193], v[94:97]
	v_mfma_f32_16x16x32_bf16 v[82:85], v[150:153], v[190:193], v[82:85]
	v_mfma_f32_16x16x32_bf16 v[78:81], v[140:143], v[198:201], v[78:81]
	v_mfma_f32_16x16x32_bf16 v[66:69], v[150:153], v[198:201], v[66:69]
	v_mfma_f32_16x16x32_bf16 v[126:129], v[146:149], v[178:181], v[126:129]
	v_mfma_f32_16x16x32_bf16 v[118:121], v[154:157], v[178:181], v[118:121]
	v_mfma_f32_16x16x32_bf16 v[106:109], v[146:149], v[186:189], v[106:109]
	v_mfma_f32_16x16x32_bf16 v[98:101], v[154:157], v[186:189], v[98:101]
	v_mfma_f32_16x16x32_bf16 v[94:97], v[146:149], v[194:197], v[94:97]
	v_mfma_f32_16x16x32_bf16 v[82:85], v[154:157], v[194:197], v[82:85]
	v_mfma_f32_16x16x32_bf16 v[78:81], v[146:149], v[202:205], v[78:81]
	v_mfma_f32_16x16x32_bf16 v[66:69], v[154:157], v[202:205], v[66:69]
	s_setprio 0
	s_setprio 1
	v_mfma_f32_16x16x32_bf16 v[122:125], v[158:161], v[174:177], v[122:125]
	v_mfma_f32_16x16x32_bf16 v[114:117], v[166:169], v[174:177], v[114:117]
	v_mfma_f32_16x16x32_bf16 v[110:113], v[158:161], v[182:185], v[110:113]
	v_mfma_f32_16x16x32_bf16 v[102:105], v[166:169], v[182:185], v[102:105]
	v_mfma_f32_16x16x32_bf16 v[90:93], v[158:161], v[190:193], v[90:93]
	v_mfma_f32_16x16x32_bf16 v[86:89], v[166:169], v[190:193], v[86:89]
	v_mfma_f32_16x16x32_bf16 v[74:77], v[158:161], v[198:201], v[74:77]
	v_mfma_f32_16x16x32_bf16 v[70:73], v[166:169], v[198:201], v[70:73]
	v_mfma_f32_16x16x32_bf16 v[122:125], v[162:165], v[178:181], v[122:125]
	v_mfma_f32_16x16x32_bf16 v[114:117], v[170:173], v[178:181], v[114:117]
	v_mfma_f32_16x16x32_bf16 v[110:113], v[162:165], v[186:189], v[110:113]
	v_mfma_f32_16x16x32_bf16 v[102:105], v[170:173], v[186:189], v[102:105]
	v_mfma_f32_16x16x32_bf16 v[90:93], v[162:165], v[194:197], v[90:93]
	v_mfma_f32_16x16x32_bf16 v[86:89], v[170:173], v[194:197], v[86:89]
	v_mfma_f32_16x16x32_bf16 v[74:77], v[162:165], v[202:205], v[74:77]
	v_mfma_f32_16x16x32_bf16 v[70:73], v[170:173], v[202:205], v[70:73]
	s_setprio 0
	s_barrier
	s_add_i32 s78, s78, s52
	v_lshl_add_u64 v[206:207], s[26:27], 0, v[0:1]
	s_mov_b32 m0, s78
	ds_read_b128 v[174:177], v145 offset:16384
	ds_read_b128 v[178:181], v145 offset:17408
	ds_read_b128 v[182:185], v145 offset:18432
	ds_read_b128 v[186:189], v145 offset:19456
	ds_read_b128 v[190:193], v145 offset:20480
	ds_read_b128 v[194:197], v145 offset:21504
	ds_read_b128 v[198:201], v145 offset:22528
	ds_read_b128 v[202:205], v145 offset:23552
	global_load_lds_dwordx4 v[206:207], off
	s_add_i32 m0, s78, 0x2000
	s_add_u32 s78, s26, 0x40000
	v_lshl_add_u64 v[208:209], s[26:27], 0, v[130:131]
	s_addc_u32 s79, s27, 0
	s_add_i32 s80, s80, s52
	global_load_lds_dwordx4 v[208:209], off
	v_lshl_add_u64 v[210:211], s[78:79], 0, v[0:1]
	s_mov_b32 m0, s80
	v_lshl_add_u64 v[220:221], s[36:37], 0, v[132:133]
	global_load_lds_dwordx4 v[210:211], off
	v_lshl_add_u64 v[210:211], s[78:79], 0, v[130:131]
	s_add_i32 m0, s80, 0x2000
	s_nop 0
	global_load_lds_dwordx4 v[210:211], off
	v_lshl_add_u64 v[210:211], s[36:37], 0, v[134:135]
	s_mov_b32 m0, s40
	s_nop 0
	global_load_lds_dwordx4 v[210:211], off
	s_mov_b32 m0, s41
	s_nop 0
	global_load_lds_dwordx4 v[220:221], off
	s_cmp_eq_u32 s82, 0
	s_cbranch_scc1 .Lrw_gu_2_w8
	s_cmp_eq_u32 s82, 1
	s_cbranch_scc1 .Lrw_gu_2_w1
	s_waitcnt vmcnt(24)
	s_branch .Lrw_gu_2_done

; #define PG8_STAGE(bufoff, gbase, voff) do { _Pragma("unroll") for (int _i = 0; _i < 2; ++_i) \
;         __builtin_amdgcn_global_load_lds((const unsigned*)((const char*)(gbase) + (voff)[_i]), (PG8_LAS unsigned*)(lds + (bufoff) + ldsw + _i * 8192), 16, 0, 0); } while (0)
; #define PG8_LDA(dst, b, h) do { _Pragma("unroll") for (int m = 0; m < 4; ++m) _Pragma("unroll") for (int k = 0; k < 2; ++k) dst[m][k] = *(const PG8_LAS bf16x8*)(lds + PG8_SA(b, h) + aoff + m * 2048 + k * 1024); } while (0)
; #define PG8_LDB(dst, b, h) do { _Pragma("unroll") for (int n = 0; n < 2; ++n) _Pragma("unroll") for (int k = 0; k < 2; ++k) dst[n][k] = *(const PG8_LAS bf16x8*)(lds + PG8_SB(b, h) + boff + n * 2048 + k * 1024); } while (0)
; #define PG8_MMA(ai, bj, At, Bt) do { __builtin_amdgcn_s_setprio(1); _Pragma("unroll") for (int m = 0; m < 4; ++m) _Pragma("unroll") for (int n = 0; n < 2; ++n) _Pragma("unroll") for (int k = 0; k < 2; ++k) \
;         acc[ai][bj][m][n] = __builtin_amdgcn_mfma_f32_16x16x32_bf16(Bt[n][k], At[m][k], acc[ai][bj][m][n], 0, 0, 0); __builtin_amdgcn_s_setprio(0); } while (0)
; #define PG8_WAIT_V(n) asm volatile("s_waitcnt vmcnt(" #n ")" ::: "memory")
; #define PG8_WAIT_L(n) asm volatile("s_waitcnt lgkmcnt(" #n ")" ::: "memory")
; #define PG8_BAR __builtin_amdgcn_s_barrier()
; #define PG8_SCHED __builtin_amdgcn_sched_barrier(0)
; template <class Epi, class Sched, bool ALIGN_EPI = false, bool SP2 = false>
; __device__ __forceinline__ void gemm_phase(PG8_LAS unsigned char* lds, const Gemm g, const Sched& S, const Epi& E) {
;     ...
;             PG8_WAIT_V(8); PG8_WAIT_L(0); PG8_BAR; PG8_MMA(1, 0, At, B0); PG8_MMA(1, 1, At, B1); PG8_BAR; PG8_SCHED;
;             PG8_LDB(B0, 1, 0); PG8_LDB(B1, 1, 1); PG8_SCHED; PG8_LDA(At, 1, 0); PG8_STAGE(PG8_SA(0, 1), a2 + hstep, voffA);
;             PG8_WAIT_V(8); PG8_WAIT_L(0); PG8_BAR; PG8_MMA(0, 0, At, B0); PG8_MMA(0, 1, At, B1); PG8_BAR; PG8_SCHED;
.Lrw_gu_2_done:
	s_mov_b32 s82, 0
	s_waitcnt lgkmcnt(0)
	s_barrier
	s_setprio 1
	s_waitcnt lgkmcnt(0)
	v_mfma_f32_16x16x32_bf16 v[62:65], v[140:143], v[174:177], v[62:65]
	v_mfma_f32_16x16x32_bf16 v[50:53], v[150:153], v[174:177], v[50:53]
	v_mfma_f32_16x16x32_bf16 v[46:49], v[140:143], v[182:185], v[46:49]
	v_mfma_f32_16x16x32_bf16 v[34:37], v[150:153], v[182:185], v[34:37]
	v_mfma_f32_16x16x32_bf16 v[30:33], v[140:143], v[190:193], v[30:33]
	v_mfma_f32_16x16x32_bf16 v[18:21], v[150:153], v[190:193], v[18:21]
	v_mfma_f32_16x16x32_bf16 v[14:17], v[140:143], v[198:201], v[14:17]
	v_mfma_f32_16x16x32_bf16 v[6:9], v[150:153], v[198:201], v[6:9]
	v_mfma_f32_16x16x32_bf16 v[62:65], v[146:149], v[178:181], v[62:65]
	v_mfma_f32_16x16x32_bf16 v[50:53], v[154:157], v[178:181], v[50:53]
	v_mfma_f32_16x16x32_bf16 v[46:49], v[146:149], v[186:189], v[46:49]
	v_mfma_f32_16x16x32_bf16 v[34:37], v[154:157], v[186:189], v[34:37]
	v_mfma_f32_16x16x32_bf16 v[30:33], v[146:149], v[194:197], v[30:33]
	v_mfma_f32_16x16x32_bf16 v[18:21], v[154:157], v[194:197], v[18:21]
	v_mfma_f32_16x16x32_bf16 v[14:17], v[146:149], v[202:205], v[14:17]
	v_mfma_f32_16x16x32_bf16 v[6:9], v[154:157], v[202:205], v[6:9]
	s_setprio 0
	s_setprio 1
	v_mfma_f32_16x16x32_bf16 v[58:61], v[158:161], v[174:177], v[58:61]
	v_mfma_f32_16x16x32_bf16 v[54:57], v[166:169], v[174:177], v[54:57]
	v_mfma_f32_16x16x32_bf16 v[42:45], v[158:161], v[182:185], v[42:45]
	v_mfma_f32_16x16x32_bf16 v[38:41], v[166:169], v[182:185], v[38:41]
	v_mfma_f32_16x16x32_bf16 v[26:29], v[158:161], v[190:193], v[26:29]
	v_mfma_f32_16x16x32_bf16 v[22:25], v[166:169], v[190:193], v[22:25]
	v_mfma_f32_16x16x32_bf16 v[10:13], v[158:161], v[198:201], v[10:13]
	v_mfma_f32_16x16x32_bf16 v[2:5], v[166:169], v[198:201], v[2:5]
	v_mfma_f32_16x16x32_bf16 v[58:61], v[162:165], v[178:181], v[58:61]
	v_mfma_f32_16x16x32_bf16 v[54:57], v[170:173], v[178:181], v[54:57]
	v_mfma_f32_16x16x32_bf16 v[42:45], v[162:165], v[186:189], v[42:45]
	v_mfma_f32_16x16x32_bf16 v[38:41], v[170:173], v[186:189], v[38:41]
	v_mfma_f32_16x16x32_bf16 v[26:29], v[162:165], v[194:197], v[26:29]
	v_mfma_f32_16x16x32_bf16 v[22:25], v[170:173], v[194:197], v[22:25]
	v_mfma_f32_16x16x32_bf16 v[10:13], v[162:165], v[202:205], v[10:13]
	v_mfma_f32_16x16x32_bf16 v[2:5], v[170:173], v[202:205], v[2:5]
	s_setprio 0
	s_barrier
	s_add_i32 s78, 0, 0x18000
	s_add_i32 s79, 0, 0x1c000
	v_add_u32_e32 v154, s78, v144
	v_add_u32_e32 v170, s79, v144
	ds_read_b128 v[140:143], v154
	ds_read_b128 v[146:149], v154 offset:1024
	ds_read_b128 v[150:153], v154 offset:2048
	ds_read_b128 v[154:157], v154 offset:3072
	ds_read_b128 v[158:161], v170
	ds_read_b128 v[162:165], v170 offset:1024
	ds_read_b128 v[166:169], v170 offset:2048
	ds_read_b128 v[170:173], v170 offset:3072
	s_add_u32 s36, s36, 0x40000
	s_addc_u32 s37, s37, 0
	s_mov_b32 m0, s53
	v_lshl_add_u64 v[222:223], s[36:37], 0, v[134:135]
	ds_read_b128 v[174:177], v145 offset:32768
	ds_read_b128 v[178:181], v145 offset:33792
	ds_read_b128 v[182:185], v145 offset:34816
	ds_read_b128 v[186:189], v145 offset:35840
	ds_read_b128 v[190:193], v145 offset:36864
	ds_read_b128 v[194:197], v145 offset:37888
	ds_read_b128 v[198:201], v145 offset:38912
	ds_read_b128 v[202:205], v145 offset:39936
	global_load_lds_dwordx4 v[222:223], off
	v_lshl_add_u64 v[222:223], s[36:37], 0, v[132:133]
	s_mov_b32 m0, s60
	s_nop 0
	global_load_lds_dwordx4 v[222:223], off
	s_waitcnt vmcnt(8)
	s_waitcnt lgkmcnt(0)
	s_barrier
	s_setprio 1
	s_waitcnt lgkmcnt(0)
	v_mfma_f32_16x16x32_bf16 v[126:129], v[140:143], v[174:177], v[126:129]
	v_mfma_f32_16x16x32_bf16 v[118:121], v[150:153], v[174:177], v[118:121]
	v_mfma_f32_16x16x32_bf16 v[106:109], v[140:143], v[182:185], v[106:109]
	v_mfma_f32_16x16x32_bf16 v[98:101], v[150:153], v[182:185], v[98:101]
	v_mfma_f32_16x16x32_bf16 v[94:97], v[140:143], v[190:193], v[94:97]
	v_mfma_f32_16x16x32_bf16 v[82:85], v[150:153], v[190:193], v[82:85]
	v_mfma_f32_16x16x32_bf16 v[78:81], v[140:143], v[198:201], v[78:81]
	v_mfma_f32_16x16x32_bf16 v[66:69], v[150:153], v[198:201], v[66:69]
	v_mfma_f32_16x16x32_bf16 v[126:129], v[146:149], v[178:181], v[126:129]
	v_mfma_f32_16x16x32_bf16 v[118:121], v[154:157], v[178:181], v[118:121]
	v_mfma_f32_16x16x32_bf16 v[106:109], v[146:149], v[186:189], v[106:109]
	v_mfma_f32_16x16x32_bf16 v[98:101], v[154:157], v[186:189], v[98:101]
	v_mfma_f32_16x16x32_bf16 v[94:97], v[146:149], v[194:197], v[94:97]
	v_mfma_f32_16x16x32_bf16 v[82:85], v[154:157], v[194:197], v[82:85]
	v_mfma_f32_16x16x32_bf16 v[78:81], v[146:149], v[202:205], v[78:81]
	v_mfma_f32_16x16x32_bf16 v[66:69], v[154:157], v[202:205], v[66:69]
	s_setprio 0
	s_setprio 1
	v_mfma_f32_16x16x32_bf16 v[122:125], v[158:161], v[174:177], v[122:125]
	v_mfma_f32_16x16x32_bf16 v[114:117], v[166:169], v[174:177], v[114:117]
	v_mfma_f32_16x16x32_bf16 v[110:113], v[158:161], v[182:185], v[110:113]
	v_mfma_f32_16x16x32_bf16 v[102:105], v[166:169], v[182:185], v[102:105]
	v_mfma_f32_16x16x32_bf16 v[90:93], v[158:161], v[190:193], v[90:93]
	v_mfma_f32_16x16x32_bf16 v[86:89], v[166:169], v[190:193], v[86:89]
	v_mfma_f32_16x16x32_bf16 v[74:77], v[158:161], v[198:201], v[74:77]
	v_mfma_f32_16x16x32_bf16 v[70:73], v[166:169], v[198:201], v[70:73]
	v_mfma_f32_16x16x32_bf16 v[122:125], v[162:165], v[178:181], v[122:125]
	v_mfma_f32_16x16x32_bf16 v[114:117], v[170:173], v[178:181], v[114:117]
	v_mfma_f32_16x16x32_bf16 v[110:113], v[162:165], v[186:189], v[110:113]
	v_mfma_f32_16x16x32_bf16 v[102:105], v[170:173], v[186:189], v[102:105]
	v_mfma_f32_16x16x32_bf16 v[90:93], v[162:165], v[194:197], v[90:93]
	v_mfma_f32_16x16x32_bf16 v[86:89], v[170:173], v[194:197], v[86:89]
	v_mfma_f32_16x16x32_bf16 v[74:77], v[162:165], v[202:205], v[74:77]
	v_mfma_f32_16x16x32_bf16 v[70:73], v[170:173], v[202:205], v[70:73]
	s_setprio 0
	s_barrier
; #define PG8_STAGE(bufoff, gbase, voff) do { _Pragma("unroll") for (int _i = 0; _i < 2; ++_i) \
;         __builtin_amdgcn_global_load_lds((const unsigned*)((const char*)(gbase) + (voff)[_i]), (PG8_LAS unsigned*)(lds + (bufoff) + ldsw + _i * 8192), 16, 0, 0); } while (0)
; #define PG8_LDA(dst, b, h) do { _Pragma("unroll") for (int m = 0; m < 4; ++m) _Pragma("unroll") for (int k = 0; k < 2; ++k) dst[m][k] = *(const PG8_LAS bf16x8*)(lds + PG8_SA(b, h) + aoff + m * 2048 + k * 1024); } while (0)
; #define PG8_MMA(ai, bj, At, Bt) do { __builtin_amdgcn_s_setprio(1); _Pragma("unroll") for (int m = 0; m < 4; ++m) _Pragma("unroll") for (int n = 0; n < 2; ++n) _Pragma("unroll") for (int k = 0; k < 2; ++k) \
;         acc[ai][bj][m][n] = __builtin_amdgcn_mfma_f32_16x16x32_bf16(Bt[n][k], At[m][k], acc[ai][bj][m][n], 0, 0, 0); __builtin_amdgcn_s_setprio(0); } while (0)
; #define PG8_WAIT_V(n) asm volatile("s_waitcnt vmcnt(" #n ")" ::: "memory")
; #define PG8_WAIT_L(n) asm volatile("s_waitcnt lgkmcnt(" #n ")" ::: "memory")
; #define PG8_BAR __builtin_amdgcn_s_barrier()
; #define PG8_SCHED __builtin_amdgcn_sched_barrier(0)
;     __device__ __forceinline__ void operator()(const f32x4 (&acc)[2][2][4][2], const Unit& u, int wr, int wc, int fr_in, int fq_in) const {
;     ...
;                 const f32x4 g0 = acc[ai][0][m][0], g1 = acc[ai][0][m][1], u0 = acc[ai][1][m][0], u1 = acc[ai][1][m][1];
;                 const f32x2 a0 = silu_mul2((f32x2){g0[0], g0[1]}, (f32x2){u0[0], u0[1]}, kneg, rs2), a1 = silu_mul2((f32x2){g0[2], g0[3]}, (f32x2){u0[2], u0[3]}, kneg, rs2);
;                 const f32x2 a2 = silu_mul2((f32x2){g1[0], g1[1]}, (f32x2){u1[0], u1[1]}, kneg, rs2), a3 = silu_mul2((f32x2){g1[2], g1[3]}, (f32x2){u1[2], u1[3]}, kneg, rs2);
; template <class Epi, class Sched, bool ALIGN_EPI = false, bool SP2 = false>
; __device__ __forceinline__ void gemm_phase(PG8_LAS unsigned char* lds, const Gemm g, const Sched& S, const Epi& E) {
;     ...
;             PG8_LDA(At, 1, 1); PG8_STAGE(PG8_SB(1, 0), b3, voffB); PG8_STAGE(PG8_SB(1, 1), b3 + hstep, voffB); PG8_STAGE(PG8_SA(1, 0), a3, voffA);
;             PG8_WAIT_V(8); PG8_WAIT_L(0); PG8_BAR; PG8_MMA(1, 0, At, B0); PG8_MMA(1, 1, At, B1); PG8_BAR; PG8_SCHED;
	s_add_i32 s36, s78, s52
	v_lshl_add_u64 v[206:207], v[206:207], 0, s[28:29]
	s_mov_b32 m0, s36
	ds_read_b128 v[174:177], v145 offset:49152
	ds_read_b128 v[178:181], v145 offset:50176
	ds_read_b128 v[182:185], v145 offset:51200
	ds_read_b128 v[186:189], v145 offset:52224
	ds_read_b128 v[190:193], v145 offset:53248
	ds_read_b128 v[194:197], v145 offset:54272
	ds_read_b128 v[198:201], v145 offset:55296
	ds_read_b128 v[202:205], v145 offset:56320
	global_load_lds_dwordx4 v[206:207], off
	s_add_i32 m0, s36, 0x2000
	s_add_u32 s26, s26, 0x40080
	v_lshl_add_u64 v[206:207], v[208:209], 0, s[28:29]
	s_addc_u32 s27, s27, 0
	s_add_i32 s36, s79, s52
	global_load_lds_dwordx4 v[206:207], off
	v_lshl_add_u64 v[206:207], s[26:27], 0, v[0:1]
	s_mov_b32 m0, s36
	s_nop 0
	global_load_lds_dwordx4 v[206:207], off
	v_lshl_add_u64 v[206:207], s[26:27], 0, v[130:131]
	s_add_i32 m0, s36, 0x2000
	s_nop 0
	global_load_lds_dwordx4 v[206:207], off
	v_lshl_add_u64 v[206:207], v[210:211], 0, s[28:29]
	s_mov_b32 m0, s65
	s_nop 0
	global_load_lds_dwordx4 v[206:207], off
	v_lshl_add_u64 v[206:207], v[220:221], 0, s[28:29]
	s_mov_b32 m0, s69
	s_nop 0
	global_load_lds_dwordx4 v[206:207], off
	s_waitcnt vmcnt(8)
	s_waitcnt lgkmcnt(0)
	s_barrier
	s_setprio 1
	s_waitcnt lgkmcnt(0)
	v_mfma_f32_16x16x32_bf16 v[62:65], v[140:143], v[174:177], v[62:65]
	v_mfma_f32_16x16x32_bf16 v[50:53], v[150:153], v[174:177], v[50:53]
	v_mfma_f32_16x16x32_bf16 v[46:49], v[140:143], v[182:185], v[46:49]
	v_mfma_f32_16x16x32_bf16 v[34:37], v[150:153], v[182:185], v[34:37]
	v_mfma_f32_16x16x32_bf16 v[30:33], v[140:143], v[190:193], v[30:33]
	v_mfma_f32_16x16x32_bf16 v[18:21], v[150:153], v[190:193], v[18:21]
	v_mfma_f32_16x16x32_bf16 v[14:17], v[140:143], v[198:201], v[14:17]
	v_mfma_f32_16x16x32_bf16 v[6:9], v[150:153], v[198:201], v[6:9]
	v_mfma_f32_16x16x32_bf16 v[62:65], v[146:149], v[178:181], v[62:65]
	v_mfma_f32_16x16x32_bf16 v[50:53], v[154:157], v[178:181], v[50:53]
	v_mfma_f32_16x16x32_bf16 v[46:49], v[146:149], v[186:189], v[46:49]
	v_mfma_f32_16x16x32_bf16 v[34:37], v[154:157], v[186:189], v[34:37]
	v_mfma_f32_16x16x32_bf16 v[30:33], v[146:149], v[194:197], v[30:33]
	v_mfma_f32_16x16x32_bf16 v[18:21], v[154:157], v[194:197], v[18:21]
	v_mfma_f32_16x16x32_bf16 v[14:17], v[146:149], v[202:205], v[14:17]
	v_mfma_f32_16x16x32_bf16 v[6:9], v[154:157], v[202:205], v[6:9]
	s_setprio 0
	s_setprio 1
	v_mfma_f32_16x16x32_bf16 v[58:61], v[158:161], v[174:177], v[58:61]
	v_mfma_f32_16x16x32_bf16 v[54:57], v[166:169], v[174:177], v[54:57]
	v_mfma_f32_16x16x32_bf16 v[42:45], v[158:161], v[182:185], v[42:45]
	v_mfma_f32_16x16x32_bf16 v[38:41], v[166:169], v[182:185], v[38:41]
	v_mfma_f32_16x16x32_bf16 v[26:29], v[158:161], v[190:193], v[26:29]
	v_mfma_f32_16x16x32_bf16 v[22:25], v[166:169], v[190:193], v[22:25]
	v_mfma_f32_16x16x32_bf16 v[10:13], v[158:161], v[198:201], v[10:13]
	v_mfma_f32_16x16x32_bf16 v[2:5], v[166:169], v[198:201], v[2:5]
	v_mfma_f32_16x16x32_bf16 v[58:61], v[162:165], v[178:181], v[58:61]
	v_mfma_f32_16x16x32_bf16 v[54:57], v[170:173], v[178:181], v[54:57]
	v_mfma_f32_16x16x32_bf16 v[42:45], v[162:165], v[186:189], v[42:45]
	v_mfma_f32_16x16x32_bf16 v[38:41], v[170:173], v[186:189], v[38:41]
	v_mfma_f32_16x16x32_bf16 v[26:29], v[162:165], v[194:197], v[26:29]
	v_mfma_f32_16x16x32_bf16 v[22:25], v[170:173], v[194:197], v[22:25]
	v_mfma_f32_16x16x32_bf16 v[10:13], v[162:165], v[202:205], v[10:13]
	v_mfma_f32_16x16x32_bf16 v[2:5], v[170:173], v[202:205], v[2:5]
	s_setprio 0
	s_barrier
	s_add_i32 s77, s77, 2
	s_add_u32 s75, s75, 0x100
	s_addc_u32 s76, s76, 0
	s_add_u32 s24, s24, 0x100
	s_addc_u32 s25, s25, 0
	s_cmp_gt_u32 s77, 13
	s_cbranch_scc0 .LBB0_178
	s_and_b64 vcc, exec, s[6:7]
	s_cbranch_vccz .LBB0_181
	s_barrier
.LBB0_181:
	s_lshl_b32 s15, s72, 8
	v_mov_b32_e32 v140, v252
	s_add_i32 s15, s15, s61
	v_pk_mul_f32 v[122:123], v[126:127], v[122:123]
	v_and_or_b32 v142, v140, 15, s15
	v_ashrrev_i32_e32 v143, 31, v142
	v_lshrrev_b32_e32 v158, 1, v140
	v_lshl_add_u64 v[140:141], v[142:143], 2, s[12:13]
	s_lshl_b32 s15, s71, 7
	v_and_or_b32 v140, v158, 24, s15
	v_or_b32_e32 v158, s64, v140
	v_ashrrev_i32_e32 v159, 31, v158
	v_or_b32_e32 v161, 16, v142
	v_or_b32_e32 v156, 32, v142
	v_or_b32_e32 v154, 48, v142
	v_add_u32_e32 v152, 0x80, v142
	v_add_u32_e32 v150, 0x90, v142
	v_add_u32_e32 v148, 0xa0, v142
	v_add_u32_e32 v146, 0xb0, v142
	v_pk_mul_f32 v[124:125], v[128:129], v[124:125]
	v_pk_mul_f32 v[114:115], v[118:119], v[114:115]
	v_pk_mul_f32 v[116:117], v[120:121], v[116:117]
	v_pk_mul_f32 v[112:113], v[108:109], v[112:113]
	v_pk_mul_f32 v[104:105], v[100:101], v[104:105]
	v_pk_mul_f32 v[90:91], v[94:95], v[90:91]
	v_pk_mul_f32 v[92:93], v[96:97], v[92:93]
	v_pk_mul_f32 v[88:89], v[84:85], v[88:89]
	v_pk_mul_f32 v[74:75], v[78:79], v[74:75]
	v_pk_mul_f32 v[76:77], v[80:81], v[76:77]
	v_pk_mul_f32 v[72:73], v[68:69], v[72:73]
	v_pk_mul_f32 v[58:59], v[62:63], v[58:59]
	v_pk_mul_f32 v[60:61], v[64:65], v[60:61]
	v_pk_mul_f32 v[56:57], v[52:53], v[56:57]
	v_pk_mul_f32 v[42:43], v[46:47], v[42:43]
	v_pk_mul_f32 v[44:45], v[48:49], v[44:45]
	v_pk_mul_f32 v[40:41], v[36:37], v[40:41]
	v_pk_mul_f32 v[26:27], v[30:31], v[26:27]
	v_pk_mul_f32 v[28:29], v[32:33], v[28:29]
	v_pk_mul_f32 v[24:25], v[20:21], v[24:25]
	v_pk_mul_f32 v[10:11], v[14:15], v[10:11]
	v_pk_mul_f32 v[12:13], v[16:17], v[12:13]
	v_pk_mul_f32 v[2:3], v[6:7], v[2:3]
	v_pk_mul_f32 v[4:5], v[8:9], v[4:5]
	s_andn2_b64 vcc, exec, s[0:1]
	s_waitcnt lgkmcnt(0)
; __device__ __forceinline__ unsigned cvt_pk_bf16(float lo, float hi) { unsigned r; asm volatile("v_cvt_pk_bf16_f32 %0, %1, %2" : "=v"(r) : "v"(lo), "v"(hi)); return r; }
; __device__ __forceinline__ float silu_mul(float g, float u) { return g * __builtin_amdgcn_rcpf(1.0f + __builtin_amdgcn_exp2f(-g * 1.4426950408889634f)) * u; }
; __device__ __forceinline__ f32x2 silu_mul2(f32x2 g, f32x2 u, float kneg, float rs2) {
;     const f32x2 t = g * kneg;
;     f32x2 e; e.x = __builtin_amdgcn_exp2f(t.x); e.y = __builtin_amdgcn_exp2f(t.y);
;     const f32x2 d = e + 1.0f;
;     f32x2 r; r.x = __builtin_amdgcn_rcpf(d.x); r.y = __builtin_amdgcn_rcpf(d.y);
;     return (g * u) * (r * rs2);
; }
;     __device__ __forceinline__ void operator()(const f32x4 (&acc)[2][2][4][2], const Unit& u, int wr, int wc, int fr_in, int fq_in) const {
;     ...
;         for (int ai = 0; ai < 2; ++ai)
; #pragma unroll
;             for (int m = 0; m < 4; ++m) {
;                 const int row = row0 + ai * HALF + m * 16;
;                 const float rs = __builtin_amdgcn_rsqf(ssv[ai][m] * (1.0f / 1024.0f) + 1e-6f);
;                 const float kneg = -1.4426950408889634f * rs, rs2 = rs * rs;
;                 bf16_t* rowp = O + (size_t)row * ldo + col0;
;                 const f32x4 g0 = acc[ai][0][m][0], g1 = acc[ai][0][m][1], u0 = acc[ai][1][m][0], u1 = acc[ai][1][m][1];
;                 const f32x2 a0 = silu_mul2((f32x2){g0[0], g0[1]}, (f32x2){u0[0], u0[1]}, kneg, rs2), a1 = silu_mul2((f32x2){g0[2], g0[3]}, (f32x2){u0[2], u0[3]}, kneg, rs2);
;                 const f32x2 a2 = silu_mul2((f32x2){g1[0], g1[1]}, (f32x2){u1[0], u1[1]}, kneg, rs2), a3 = silu_mul2((f32x2){g1[2], g1[3]}, (f32x2){u1[2], u1[3]}, kneg, rs2);
;                 u32x4 w; w.x = cvt_pk_bf16(a0.x, a0.y); w.y = cvt_pk_bf16(a1.x, a1.y); w.z = cvt_pk_bf16(a2.x, a2.y); w.w = cvt_pk_bf16(a3.x, a3.y);
;                 *(u32x4*)rowp = w;
	v_fmamk_f32 v140, v232, 0x3a800000, v218
	v_rsq_f32_e32 v140, v140
	s_nop 0
	v_mul_f32_e32 v160, 0xbfb8aa3b, v140
	v_mul_f32_e32 v162, v140, v140
	v_mov_b64_e32 v[140:141], s[16:17]
	v_mad_i64_i32 v[164:165], s[24:25], v142, s55, v[140:141]
	v_lshlrev_b64 v[142:143], 1, v[158:159]
	v_lshl_add_u64 v[158:159], v[164:165], 0, v[142:143]
	v_pk_mul_f32 v[164:165], v[126:127], v[160:161] op_sel_hi:[1,0]
	s_nop 0
	v_exp_f32_e32 v164, v164
	v_exp_f32_e32 v165, v165
	s_nop 0
	v_pk_add_f32 v[164:165], v[164:165], 1.0 op_sel_hi:[1,0]
	s_nop 0
	v_rcp_f32_e32 v164, v164
	v_rcp_f32_e32 v165, v165
	s_nop 0
	v_pk_mul_f32 v[126:127], v[162:163], v[164:165] op_sel_hi:[0,1]
	v_pk_mul_f32 v[122:123], v[122:123], v[126:127]
	v_pk_mul_f32 v[126:127], v[128:129], v[160:161] op_sel_hi:[1,0]
	s_nop 0
	v_exp_f32_e32 v126, v126
	v_exp_f32_e32 v127, v127
	s_nop 0
	v_pk_add_f32 v[126:127], v[126:127], 1.0 op_sel_hi:[1,0]
	s_nop 0
	v_rcp_f32_e32 v126, v126
	v_rcp_f32_e32 v127, v127
	s_nop 0
	v_pk_mul_f32 v[126:127], v[162:163], v[126:127] op_sel_hi:[0,1]
	v_pk_mul_f32 v[124:125], v[124:125], v[126:127]
	v_pk_mul_f32 v[126:127], v[118:119], v[160:161] op_sel_hi:[1,0]
	s_nop 0
	v_exp_f32_e32 v126, v126
	v_exp_f32_e32 v127, v127
	s_nop 0
	v_pk_add_f32 v[126:127], v[126:127], 1.0 op_sel_hi:[1,0]
	s_nop 0
	v_rcp_f32_e32 v126, v126
	v_rcp_f32_e32 v127, v127
	s_nop 0
	v_pk_mul_f32 v[118:119], v[162:163], v[126:127] op_sel_hi:[0,1]
	v_pk_mul_f32 v[118:119], v[114:115], v[118:119]
	v_pk_mul_f32 v[114:115], v[120:121], v[160:161] op_sel_hi:[1,0]
	s_nop 0
	v_exp_f32_e32 v114, v114
	v_exp_f32_e32 v115, v115
	s_nop 0
	v_pk_add_f32 v[114:115], v[114:115], 1.0 op_sel_hi:[1,0]
	s_nop 0
	v_rcp_f32_e32 v114, v114
	v_rcp_f32_e32 v115, v115
	s_nop 0
	v_pk_mul_f32 v[114:115], v[162:163], v[114:115] op_sel_hi:[0,1]
	v_pk_mul_f32 v[120:121], v[116:117], v[114:115]
	v_cvt_pk_bf16_f32 v114, v122, v123
	v_cvt_pk_bf16_f32 v115, v124, v125
	v_cvt_pk_bf16_f32 v116, v118, v119
	s_nop 0
	v_cvt_pk_bf16_f32 v117, v120, v121
	flat_store_dwordx4 v[158:159], v[114:117]
	s_nop 1
	v_fmamk_f32 v114, v233, 0x3a800000, v218
	v_rsq_f32_e32 v114, v114
	s_nop 0
	v_mul_f32_e32 v118, 0xbfb8aa3b, v114
	v_pk_mul_f32 v[120:121], v[106:107], v[118:119] op_sel_hi:[1,0]
	v_mul_f32_e32 v116, v114, v114
	v_exp_f32_e32 v120, v120
	v_exp_f32_e32 v121, v121
	v_pk_mul_f32 v[106:107], v[106:107], v[110:111]
	v_pk_mul_f32 v[108:109], v[108:109], v[118:119] op_sel_hi:[1,0]
	v_mad_i64_i32 v[114:115], s[24:25], v161, s55, v[140:141]
	v_pk_add_f32 v[120:121], v[120:121], 1.0 op_sel_hi:[1,0]
	v_exp_f32_e32 v108, v108
	v_rcp_f32_e32 v120, v120
	v_rcp_f32_e32 v121, v121
	v_exp_f32_e32 v109, v109
	v_lshl_add_u64 v[114:115], v[114:115], 0, v[142:143]
	v_pk_mul_f32 v[110:111], v[116:117], v[120:121] op_sel_hi:[0,1]
	v_pk_mul_f32 v[106:107], v[106:107], v[110:111]
	v_pk_mul_f32 v[110:111], v[98:99], v[118:119] op_sel_hi:[1,0]
	v_pk_mul_f32 v[98:99], v[98:99], v[102:103]
	v_exp_f32_e32 v110, v110
	v_exp_f32_e32 v111, v111
	v_pk_add_f32 v[108:109], v[108:109], 1.0 op_sel_hi:[1,0]
	v_pk_add_f32 v[110:111], v[110:111], 1.0 op_sel_hi:[1,0]
	s_nop 0
	v_rcp_f32_e32 v110, v110
	v_rcp_f32_e32 v111, v111
	v_rcp_f32_e32 v108, v108
	v_rcp_f32_e32 v109, v109
	v_pk_mul_f32 v[102:103], v[116:117], v[110:111] op_sel_hi:[0,1]
	v_pk_mul_f32 v[102:103], v[98:99], v[102:103]
	v_pk_mul_f32 v[98:99], v[100:101], v[118:119] op_sel_hi:[1,0]
	v_pk_mul_f32 v[108:109], v[116:117], v[108:109] op_sel_hi:[0,1]
	v_exp_f32_e32 v98, v98
	v_exp_f32_e32 v99, v99
	v_pk_mul_f32 v[108:109], v[112:113], v[108:109]
	v_pk_add_f32 v[98:99], v[98:99], 1.0 op_sel_hi:[1,0]
	s_nop 0
	v_rcp_f32_e32 v98, v98
	v_rcp_f32_e32 v99, v99
	s_nop 0
	v_pk_mul_f32 v[98:99], v[116:117], v[98:99] op_sel_hi:[0,1]
	v_pk_mul_f32 v[104:105], v[104:105], v[98:99]
	v_cvt_pk_bf16_f32 v98, v106, v107
	v_cvt_pk_bf16_f32 v99, v108, v109
	v_cvt_pk_bf16_f32 v100, v102, v103
	v_mad_i64_i32 v[102:103], s[24:25], v156, s55, v[140:141]
	v_cvt_pk_bf16_f32 v101, v104, v105
	flat_store_dwordx4 v[114:115], v[98:101]
	v_lshl_add_u64 v[102:103], v[102:103], 0, v[142:143]
	s_nop 0
	v_fmamk_f32 v98, v234, 0x3a800000, v218
	v_rsq_f32_e32 v99, v98
	s_nop 0
	v_mul_f32_e32 v98, 0xbfb8aa3b, v99
	v_pk_mul_f32 v[104:105], v[94:95], v[98:99] op_sel_hi:[1,0]
	v_mul_f32_e32 v100, v99, v99
	v_exp_f32_e32 v104, v104
	v_exp_f32_e32 v105, v105
	s_nop 0
	v_pk_add_f32 v[104:105], v[104:105], 1.0 op_sel_hi:[1,0]
	s_nop 0
	v_rcp_f32_e32 v104, v104
	v_rcp_f32_e32 v105, v105
	s_nop 0
	v_pk_mul_f32 v[94:95], v[100:101], v[104:105] op_sel_hi:[0,1]
	v_pk_mul_f32 v[90:91], v[90:91], v[94:95]
	v_pk_mul_f32 v[94:95], v[96:97], v[98:99] op_sel_hi:[1,0]
	s_nop 0
	v_exp_f32_e32 v94, v94
	v_exp_f32_e32 v95, v95
	s_nop 0
	v_pk_add_f32 v[94:95], v[94:95], 1.0 op_sel_hi:[1,0]
	s_nop 0
	v_rcp_f32_e32 v94, v94
	v_rcp_f32_e32 v95, v95
	s_nop 0
	v_pk_mul_f32 v[94:95], v[100:101], v[94:95] op_sel_hi:[0,1]
	v_pk_mul_f32 v[92:93], v[92:93], v[94:95]
	v_pk_mul_f32 v[94:95], v[82:83], v[98:99] op_sel_hi:[1,0]
	v_pk_mul_f32 v[82:83], v[82:83], v[86:87]
	v_exp_f32_e32 v94, v94
	v_exp_f32_e32 v95, v95
	s_nop 0
	v_pk_add_f32 v[94:95], v[94:95], 1.0 op_sel_hi:[1,0]
	s_nop 0
	v_rcp_f32_e32 v94, v94
	v_rcp_f32_e32 v95, v95
	s_nop 0
	v_pk_mul_f32 v[86:87], v[100:101], v[94:95] op_sel_hi:[0,1]
	v_pk_mul_f32 v[86:87], v[82:83], v[86:87]
	v_pk_mul_f32 v[82:83], v[84:85], v[98:99] op_sel_hi:[1,0]
	s_nop 0
	v_exp_f32_e32 v82, v82
	v_exp_f32_e32 v83, v83
	s_nop 0
	v_pk_add_f32 v[82:83], v[82:83], 1.0 op_sel_hi:[1,0]
	s_nop 0
	v_rcp_f32_e32 v82, v82
	v_rcp_f32_e32 v83, v83
	s_nop 0
	v_pk_mul_f32 v[82:83], v[100:101], v[82:83] op_sel_hi:[0,1]
	v_pk_mul_f32 v[88:89], v[88:89], v[82:83]
; __device__ __forceinline__ unsigned cvt_pk_bf16(float lo, float hi) { unsigned r; asm volatile("v_cvt_pk_bf16_f32 %0, %1, %2" : "=v"(r) : "v"(lo), "v"(hi)); return r; }
;     __device__ __forceinline__ void operator()(const f32x4 (&acc)[2][2][4][2], const Unit& u, int wr, int wc, int fr_in, int fq_in) const {
;     ...
;             for (int m = 0; m < 4; ++m) {
;                 const int row = row0 + ai * HALF + m * 16;
;                 const float rs = __builtin_amdgcn_rsqf(ssv[ai][m] * (1.0f / 1024.0f) + 1e-6f);
;                 const float kneg = -1.4426950408889634f * rs, rs2 = rs * rs;
;                 bf16_t* rowp = O + (size_t)row * ldo + col0;
;                 const f32x4 g0 = acc[ai][0][m][0], g1 = acc[ai][0][m][1], u0 = acc[ai][1][m][0], u1 = acc[ai][1][m][1];
;                 const f32x2 a0 = silu_mul2((f32x2){g0[0], g0[1]}, (f32x2){u0[0], u0[1]}, kneg, rs2), a1 = silu_mul2((f32x2){g0[2], g0[3]}, (f32x2){u0[2], u0[3]}, kneg, rs2);
;                 const f32x2 a2 = silu_mul2((f32x2){g1[0], g1[1]}, (f32x2){u1[0], u1[1]}, kneg, rs2), a3 = silu_mul2((f32x2){g1[2], g1[3]}, (f32x2){u1[2], u1[3]}, kneg, rs2);
;                 u32x4 w; w.x = cvt_pk_bf16(a0.x, a0.y); w.y = cvt_pk_bf16(a1.x, a1.y); w.z = cvt_pk_bf16(a2.x, a2.y); w.w = cvt_pk_bf16(a3.x, a3.y);
;                 *(u32x4*)rowp = w;
	v_cvt_pk_bf16_f32 v82, v90, v91
	v_cvt_pk_bf16_f32 v83, v92, v93
	v_cvt_pk_bf16_f32 v84, v86, v87
	v_mad_i64_i32 v[86:87], s[24:25], v154, s55, v[140:141]
	v_cvt_pk_bf16_f32 v85, v88, v89
	flat_store_dwordx4 v[102:103], v[82:85]
	v_lshl_add_u64 v[86:87], v[86:87], 0, v[142:143]
	s_nop 0
	v_fmamk_f32 v82, v235, 0x3a800000, v218
	v_rsq_f32_e32 v83, v82
	s_nop 0
	v_mul_f32_e32 v82, 0xbfb8aa3b, v83
	v_pk_mul_f32 v[88:89], v[78:79], v[82:83] op_sel_hi:[1,0]
	v_mul_f32_e32 v84, v83, v83
	v_exp_f32_e32 v88, v88
	v_exp_f32_e32 v89, v89
	s_nop 0
	v_pk_add_f32 v[88:89], v[88:89], 1.0 op_sel_hi:[1,0]
	s_nop 0
	v_rcp_f32_e32 v88, v88
	v_rcp_f32_e32 v89, v89
	s_nop 0
	v_pk_mul_f32 v[78:79], v[84:85], v[88:89] op_sel_hi:[0,1]
	v_pk_mul_f32 v[74:75], v[74:75], v[78:79]
	v_pk_mul_f32 v[78:79], v[80:81], v[82:83] op_sel_hi:[1,0]
	s_nop 0
	v_exp_f32_e32 v78, v78
	v_exp_f32_e32 v79, v79
	s_nop 0
	v_pk_add_f32 v[78:79], v[78:79], 1.0 op_sel_hi:[1,0]
	s_nop 0
	v_rcp_f32_e32 v78, v78
	v_rcp_f32_e32 v79, v79
	s_nop 0
	v_pk_mul_f32 v[78:79], v[84:85], v[78:79] op_sel_hi:[0,1]
	v_pk_mul_f32 v[76:77], v[76:77], v[78:79]
	v_pk_mul_f32 v[78:79], v[66:67], v[82:83] op_sel_hi:[1,0]
	v_pk_mul_f32 v[66:67], v[66:67], v[70:71]
	v_exp_f32_e32 v78, v78
	v_exp_f32_e32 v79, v79
	s_nop 0
	v_pk_add_f32 v[78:79], v[78:79], 1.0 op_sel_hi:[1,0]
	s_nop 0
	v_rcp_f32_e32 v78, v78
	v_rcp_f32_e32 v79, v79
	s_nop 0
	v_pk_mul_f32 v[70:71], v[84:85], v[78:79] op_sel_hi:[0,1]
	v_pk_mul_f32 v[70:71], v[66:67], v[70:71]
	v_pk_mul_f32 v[66:67], v[68:69], v[82:83] op_sel_hi:[1,0]
	s_nop 0
	v_exp_f32_e32 v66, v66
	v_exp_f32_e32 v67, v67
	s_nop 0
	v_pk_add_f32 v[66:67], v[66:67], 1.0 op_sel_hi:[1,0]
	s_nop 0
	v_rcp_f32_e32 v66, v66
	v_rcp_f32_e32 v67, v67
	s_nop 0
	v_pk_mul_f32 v[66:67], v[84:85], v[66:67] op_sel_hi:[0,1]
	v_pk_mul_f32 v[72:73], v[72:73], v[66:67]
	v_cvt_pk_bf16_f32 v66, v74, v75
	v_cvt_pk_bf16_f32 v67, v76, v77
	v_cvt_pk_bf16_f32 v68, v70, v71
	v_mad_i64_i32 v[70:71], s[24:25], v152, s55, v[140:141]
	v_cvt_pk_bf16_f32 v69, v72, v73
	flat_store_dwordx4 v[86:87], v[66:69]
	v_lshl_add_u64 v[70:71], v[70:71], 0, v[142:143]
	s_nop 0
	v_fmamk_f32 v66, v236, 0x3a800000, v218
	v_rsq_f32_e32 v67, v66
	s_nop 0
	v_mul_f32_e32 v66, 0xbfb8aa3b, v67
	v_pk_mul_f32 v[72:73], v[62:63], v[66:67] op_sel_hi:[1,0]
	v_mul_f32_e32 v68, v67, v67
	v_exp_f32_e32 v72, v72
	v_exp_f32_e32 v73, v73
	s_nop 0
	v_pk_add_f32 v[72:73], v[72:73], 1.0 op_sel_hi:[1,0]
	s_nop 0
	v_rcp_f32_e32 v72, v72
	v_rcp_f32_e32 v73, v73
	s_nop 0
	v_pk_mul_f32 v[62:63], v[68:69], v[72:73] op_sel_hi:[0,1]
	v_pk_mul_f32 v[58:59], v[58:59], v[62:63]
	v_pk_mul_f32 v[62:63], v[64:65], v[66:67] op_sel_hi:[1,0]
	s_nop 0
	v_exp_f32_e32 v62, v62
	v_exp_f32_e32 v63, v63
	s_nop 0
	v_pk_add_f32 v[62:63], v[62:63], 1.0 op_sel_hi:[1,0]
	s_nop 0
	v_rcp_f32_e32 v62, v62
	v_rcp_f32_e32 v63, v63
	s_nop 0
	v_pk_mul_f32 v[62:63], v[68:69], v[62:63] op_sel_hi:[0,1]
	v_pk_mul_f32 v[60:61], v[60:61], v[62:63]
	v_pk_mul_f32 v[62:63], v[50:51], v[66:67] op_sel_hi:[1,0]
	v_pk_mul_f32 v[50:51], v[50:51], v[54:55]
	v_exp_f32_e32 v62, v62
	v_exp_f32_e32 v63, v63
	s_nop 0
	v_pk_add_f32 v[62:63], v[62:63], 1.0 op_sel_hi:[1,0]
	s_nop 0
	v_rcp_f32_e32 v62, v62
	v_rcp_f32_e32 v63, v63
	s_nop 0
	v_pk_mul_f32 v[54:55], v[68:69], v[62:63] op_sel_hi:[0,1]
	v_pk_mul_f32 v[54:55], v[50:51], v[54:55]
	v_pk_mul_f32 v[50:51], v[52:53], v[66:67] op_sel_hi:[1,0]
	s_nop 0
	v_exp_f32_e32 v50, v50
	v_exp_f32_e32 v51, v51
	s_nop 0
	v_pk_add_f32 v[50:51], v[50:51], 1.0 op_sel_hi:[1,0]
	s_nop 0
	v_rcp_f32_e32 v50, v50
	v_rcp_f32_e32 v51, v51
	s_nop 0
	v_pk_mul_f32 v[50:51], v[68:69], v[50:51] op_sel_hi:[0,1]
	v_pk_mul_f32 v[56:57], v[56:57], v[50:51]
	v_cvt_pk_bf16_f32 v50, v58, v59
	v_cvt_pk_bf16_f32 v51, v60, v61
	v_cvt_pk_bf16_f32 v52, v54, v55
	v_mad_i64_i32 v[54:55], s[24:25], v150, s55, v[140:141]
	v_cvt_pk_bf16_f32 v53, v56, v57
	flat_store_dwordx4 v[70:71], v[50:53]
	v_lshl_add_u64 v[54:55], v[54:55], 0, v[142:143]
	s_nop 0
	v_fmamk_f32 v50, v237, 0x3a800000, v218
	v_rsq_f32_e32 v51, v50
	s_nop 0
	v_mul_f32_e32 v50, 0xbfb8aa3b, v51
	v_pk_mul_f32 v[56:57], v[46:47], v[50:51] op_sel_hi:[1,0]
	v_mul_f32_e32 v52, v51, v51
	v_exp_f32_e32 v56, v56
	v_exp_f32_e32 v57, v57
	s_nop 0
	v_pk_add_f32 v[56:57], v[56:57], 1.0 op_sel_hi:[1,0]
	s_nop 0
	v_rcp_f32_e32 v56, v56
	v_rcp_f32_e32 v57, v57
	s_nop 0
	v_pk_mul_f32 v[46:47], v[52:53], v[56:57] op_sel_hi:[0,1]
	v_pk_mul_f32 v[42:43], v[42:43], v[46:47]
	v_pk_mul_f32 v[46:47], v[48:49], v[50:51] op_sel_hi:[1,0]
	s_nop 0
	v_exp_f32_e32 v46, v46
	v_exp_f32_e32 v47, v47
	s_nop 0
	v_pk_add_f32 v[46:47], v[46:47], 1.0 op_sel_hi:[1,0]
	s_nop 0
	v_rcp_f32_e32 v46, v46
	v_rcp_f32_e32 v47, v47
	s_nop 0
	v_pk_mul_f32 v[46:47], v[52:53], v[46:47] op_sel_hi:[0,1]
; __device__ __forceinline__ unsigned cvt_pk_bf16(float lo, float hi) { unsigned r; asm volatile("v_cvt_pk_bf16_f32 %0, %1, %2" : "=v"(r) : "v"(lo), "v"(hi)); return r; }
; #define PG8_BAR __builtin_amdgcn_s_barrier()
;     __device__ __forceinline__ void operator()(const f32x4 (&acc)[2][2][4][2], const Unit& u, int wr, int wc, int fr_in, int fq_in) const {
;     ...
;             for (int m = 0; m < 4; ++m) {
;                 const int row = row0 + ai * HALF + m * 16;
;                 const float rs = __builtin_amdgcn_rsqf(ssv[ai][m] * (1.0f / 1024.0f) + 1e-6f);
;                 const float kneg = -1.4426950408889634f * rs, rs2 = rs * rs;
;                 bf16_t* rowp = O + (size_t)row * ldo + col0;
;                 const f32x4 g0 = acc[ai][0][m][0], g1 = acc[ai][0][m][1], u0 = acc[ai][1][m][0], u1 = acc[ai][1][m][1];
;                 const f32x2 a0 = silu_mul2((f32x2){g0[0], g0[1]}, (f32x2){u0[0], u0[1]}, kneg, rs2), a1 = silu_mul2((f32x2){g0[2], g0[3]}, (f32x2){u0[2], u0[3]}, kneg, rs2);
;                 const f32x2 a2 = silu_mul2((f32x2){g1[0], g1[1]}, (f32x2){u1[0], u1[1]}, kneg, rs2), a3 = silu_mul2((f32x2){g1[2], g1[3]}, (f32x2){u1[2], u1[3]}, kneg, rs2);
;                 u32x4 w; w.x = cvt_pk_bf16(a0.x, a0.y); w.y = cvt_pk_bf16(a1.x, a1.y); w.z = cvt_pk_bf16(a2.x, a2.y); w.w = cvt_pk_bf16(a3.x, a3.y);
;                 *(u32x4*)rowp = w;
; template <class Epi, class Sched, bool ALIGN_EPI = false, bool SP2 = false>
; __device__ __forceinline__ void gemm_phase(PG8_LAS unsigned char* lds, const Gemm g, const Sched& S, const Epi& E) {
;     ...
;         if constexpr (!Epi::AFTER_DRAIN) { E(acc, cur, wr, wc, fr, fq); S.done(cur); }
;         if (!has_next) break;
; #pragma unroll
;         for (int a = 0; a < 2; ++a)
; #pragma unroll
;             for (int b = 0; b < 2; ++b)
; #pragma unroll
;                 for (int m = 0; m < 4; ++m)
; #pragma unroll
;                     for (int n = 0; n < 2; ++n) acc[a][b][m][n] = (f32x4){0.f, 0.f, 0.f, 0.f};
;         cur = nxt; cA = nA; cB = nB; ++ui;
;         if constexpr (ALIGN_EPI) { if (wr == 1) PG8_BAR; }
;     }
	v_pk_mul_f32 v[44:45], v[44:45], v[46:47]
	v_pk_mul_f32 v[46:47], v[34:35], v[50:51] op_sel_hi:[1,0]
	v_pk_mul_f32 v[34:35], v[34:35], v[38:39]
	v_exp_f32_e32 v46, v46
	v_exp_f32_e32 v47, v47
	s_nop 0
	v_pk_add_f32 v[46:47], v[46:47], 1.0 op_sel_hi:[1,0]
	s_nop 0
	v_rcp_f32_e32 v46, v46
	v_rcp_f32_e32 v47, v47
	s_nop 0
	v_pk_mul_f32 v[38:39], v[52:53], v[46:47] op_sel_hi:[0,1]
	v_pk_mul_f32 v[38:39], v[34:35], v[38:39]
	v_pk_mul_f32 v[34:35], v[36:37], v[50:51] op_sel_hi:[1,0]
	s_nop 0
	v_exp_f32_e32 v34, v34
	v_exp_f32_e32 v35, v35
	s_nop 0
	v_pk_add_f32 v[34:35], v[34:35], 1.0 op_sel_hi:[1,0]
	s_nop 0
	v_rcp_f32_e32 v34, v34
	v_rcp_f32_e32 v35, v35
	s_nop 0
	v_pk_mul_f32 v[34:35], v[52:53], v[34:35] op_sel_hi:[0,1]
	v_pk_mul_f32 v[40:41], v[40:41], v[34:35]
	v_cvt_pk_bf16_f32 v34, v42, v43
	v_cvt_pk_bf16_f32 v35, v44, v45
	v_cvt_pk_bf16_f32 v36, v38, v39
	v_mad_i64_i32 v[38:39], s[24:25], v148, s55, v[140:141]
	v_cvt_pk_bf16_f32 v37, v40, v41
	flat_store_dwordx4 v[54:55], v[34:37]
	v_lshl_add_u64 v[38:39], v[38:39], 0, v[142:143]
	s_nop 0
	v_fmamk_f32 v34, v238, 0x3a800000, v218
	v_rsq_f32_e32 v35, v34
	s_nop 0
	v_mul_f32_e32 v34, 0xbfb8aa3b, v35
	v_pk_mul_f32 v[40:41], v[30:31], v[34:35] op_sel_hi:[1,0]
	v_mul_f32_e32 v36, v35, v35
	v_exp_f32_e32 v40, v40
	v_exp_f32_e32 v41, v41
	s_nop 0
	v_pk_add_f32 v[40:41], v[40:41], 1.0 op_sel_hi:[1,0]
	s_nop 0
	v_rcp_f32_e32 v40, v40
	v_rcp_f32_e32 v41, v41
	s_nop 0
	v_pk_mul_f32 v[30:31], v[36:37], v[40:41] op_sel_hi:[0,1]
	v_pk_mul_f32 v[26:27], v[26:27], v[30:31]
	v_pk_mul_f32 v[30:31], v[32:33], v[34:35] op_sel_hi:[1,0]
	s_nop 0
	v_exp_f32_e32 v30, v30
	v_exp_f32_e32 v31, v31
	s_nop 0
	v_pk_add_f32 v[30:31], v[30:31], 1.0 op_sel_hi:[1,0]
	s_nop 0
	v_rcp_f32_e32 v30, v30
	v_rcp_f32_e32 v31, v31
	s_nop 0
	v_pk_mul_f32 v[30:31], v[36:37], v[30:31] op_sel_hi:[0,1]
	v_pk_mul_f32 v[28:29], v[28:29], v[30:31]
	v_pk_mul_f32 v[30:31], v[18:19], v[34:35] op_sel_hi:[1,0]
	v_pk_mul_f32 v[18:19], v[18:19], v[22:23]
	v_exp_f32_e32 v30, v30
	v_exp_f32_e32 v31, v31
	s_nop 0
	v_pk_add_f32 v[30:31], v[30:31], 1.0 op_sel_hi:[1,0]
	s_nop 0
	v_rcp_f32_e32 v30, v30
	v_rcp_f32_e32 v31, v31
	s_nop 0
	v_pk_mul_f32 v[22:23], v[36:37], v[30:31] op_sel_hi:[0,1]
	v_pk_mul_f32 v[22:23], v[18:19], v[22:23]
	v_pk_mul_f32 v[18:19], v[20:21], v[34:35] op_sel_hi:[1,0]
	s_nop 0
	v_exp_f32_e32 v18, v18
	v_exp_f32_e32 v19, v19
	s_nop 0
	v_pk_add_f32 v[18:19], v[18:19], 1.0 op_sel_hi:[1,0]
	s_nop 0
	v_rcp_f32_e32 v18, v18
	v_rcp_f32_e32 v19, v19
	s_nop 0
	v_pk_mul_f32 v[18:19], v[36:37], v[18:19] op_sel_hi:[0,1]
	v_pk_mul_f32 v[24:25], v[24:25], v[18:19]
	v_cvt_pk_bf16_f32 v18, v26, v27
	v_cvt_pk_bf16_f32 v19, v28, v29
	v_cvt_pk_bf16_f32 v20, v22, v23
	v_mad_i64_i32 v[22:23], s[24:25], v146, s55, v[140:141]
	v_cvt_pk_bf16_f32 v21, v24, v25
	flat_store_dwordx4 v[38:39], v[18:21]
	v_lshl_add_u64 v[22:23], v[22:23], 0, v[142:143]
	s_mov_b64 s[24:25], -1
	v_fmamk_f32 v18, v239, 0x3a800000, v218
	v_rsq_f32_e32 v19, v18
	s_nop 0
	v_mul_f32_e32 v18, 0xbfb8aa3b, v19
	v_pk_mul_f32 v[24:25], v[14:15], v[18:19] op_sel_hi:[1,0]
	v_mul_f32_e32 v20, v19, v19
	v_exp_f32_e32 v24, v24
	v_exp_f32_e32 v25, v25
	s_nop 0
	v_pk_add_f32 v[24:25], v[24:25], 1.0 op_sel_hi:[1,0]
	s_nop 0
	v_rcp_f32_e32 v24, v24
	v_rcp_f32_e32 v25, v25
	s_nop 0
	v_pk_mul_f32 v[14:15], v[20:21], v[24:25] op_sel_hi:[0,1]
	v_pk_mul_f32 v[10:11], v[10:11], v[14:15]
	v_pk_mul_f32 v[14:15], v[16:17], v[18:19] op_sel_hi:[1,0]
	s_nop 0
	v_exp_f32_e32 v14, v14
	v_exp_f32_e32 v15, v15
	s_nop 0
	v_pk_add_f32 v[14:15], v[14:15], 1.0 op_sel_hi:[1,0]
	s_nop 0
	v_rcp_f32_e32 v14, v14
	v_rcp_f32_e32 v15, v15
	s_nop 0
	v_pk_mul_f32 v[14:15], v[20:21], v[14:15] op_sel_hi:[0,1]
	v_pk_mul_f32 v[12:13], v[12:13], v[14:15]
	v_pk_mul_f32 v[14:15], v[6:7], v[18:19] op_sel_hi:[1,0]
	s_nop 0
	v_exp_f32_e32 v14, v14
	v_exp_f32_e32 v15, v15
	s_nop 0
	v_pk_add_f32 v[14:15], v[14:15], 1.0 op_sel_hi:[1,0]
	s_nop 0
	v_rcp_f32_e32 v14, v14
	v_rcp_f32_e32 v15, v15
	s_nop 0
	v_pk_mul_f32 v[6:7], v[20:21], v[14:15] op_sel_hi:[0,1]
	v_pk_mul_f32 v[6:7], v[2:3], v[6:7]
	v_pk_mul_f32 v[2:3], v[8:9], v[18:19] op_sel_hi:[1,0]
	s_nop 0
	v_exp_f32_e32 v2, v2
	v_exp_f32_e32 v3, v3
	s_nop 0
	v_pk_add_f32 v[2:3], v[2:3], 1.0 op_sel_hi:[1,0]
	s_nop 0
	v_rcp_f32_e32 v2, v2
	v_rcp_f32_e32 v3, v3
	s_nop 0
	v_pk_mul_f32 v[2:3], v[20:21], v[2:3] op_sel_hi:[0,1]
	v_pk_mul_f32 v[8:9], v[4:5], v[2:3]
	v_cvt_pk_bf16_f32 v2, v10, v11
	v_cvt_pk_bf16_f32 v3, v12, v13
	v_cvt_pk_bf16_f32 v4, v6, v7
	s_nop 0
	v_cvt_pk_bf16_f32 v5, v8, v9
	flat_store_dwordx4 v[22:23], v[2:5]
	s_mov_b32 s83, 2
	s_cbranch_vccnz .LBB0_170
	s_andn2_b64 vcc, exec, s[10:11]
	s_cbranch_vccnz .LBB0_169
	s_barrier
	s_branch .LBB0_169
